# speedup vs baseline: 1.0103x; 1.0103x over previous
; __device__ __forceinline__ int crow(int r, int hi) { return (r & 3) + 8 * (r >> 2) + 4 * hi; }
; __device__ __forceinline__ void merge_phase(char* lds, const Bases& bs, const float* nrm, const int tid, const int bid) {
;     ...
;         for (int sg = kf; sg <= kl; ++sg) {
;             const float* po = slot_po(bs, s0 + sg) + (size_t)wid * (QBLK * D) + (unsigned)lane;
;             const float* ml = bs.ML + (size_t)(s0 + sg) * 512 + wid * QBLK;
; #pragma unroll
;             for (int r = 0; r < 16; ++r) { const int row = crow(r, hi); const float ms = ml[row], ls = ml[256 + row];
;                 if (sg == kf) { mm[r] = ms; den[r] = ls;
; #pragma unroll
;                     for (int d0 = 0; d0 < 4; ++d0) o[d0][r] = po[(d0 * 16 + r) * 64]; }
;                 else { const float mn = fmaxf(mm[r], ms), ca = __builtin_amdgcn_exp2f((mm[r] - mn) * C2), cb = __builtin_amdgcn_exp2f((ms - mn) * C2);
;                     mm[r] = mn; den[r] = den[r] * ca + cb * ls;
; #pragma unroll
;                     for (int d0 = 0; d0 < 4; ++d0) o[d0][r] = o[d0][r] * ca + cb * po[(d0 * 16 + r) * 64]; } }
;         }
.LBB0_113:
	s_add_i32 s6, s8, s20
	s_add_i32 s11, s20, 1
	s_add_i32 s7, s6, 1
	s_addk_i32 s6, 0xfe01
	s_cmpk_lt_i32 s7, 0x200
	s_cselect_b32 s7, s10, 0
	s_cselect_b32 s6, s9, s6
	s_cselect_b32 s20, s29, s31
	s_cselect_b32 s21, s28, s30
	s_lshl_b64 s[6:7], s[6:7], 17
	s_add_u32 s6, s21, s6
	global_load_dwordx4 v[32:35], v[44:45], off
	s_addc_u32 s7, s20, s7
	s_add_u32 s6, s6, s16
	s_addc_u32 s7, s7, s17
	v_lshl_add_u64 v[46:47], s[6:7], 0, v[180:181]
	v_add_co_u32_e32 v124, vcc, s22, v46
	global_load_dword v126, v180, s[6:7]
	s_nop 0
	v_addc_co_u32_e32 v125, vcc, 0, v47, vcc
	v_add_co_u32_e32 v122, vcc, s23, v46
	s_waitcnt vmcnt(2)
	v_max_f32_e32 v37, v28, v28
	v_addc_co_u32_e32 v123, vcc, 0, v47, vcc
	global_load_dword v128, v[122:123], off offset:-4096
	global_load_dword v134, v[122:123], off
	global_load_dwordx4 v[130:133], v[44:45], off offset:1024
	global_load_dword v127, v180, s[6:7] offset:256
	global_load_dword v129, v[124:125], off offset:256
	global_load_dword v135, v[122:123], off offset:256
	v_add_co_u32_e32 v46, vcc, s24, v46
	s_add_u32 s9, s9, 1
	s_nop 0
	v_addc_co_u32_e32 v47, vcc, 0, v47, vcc
	global_load_dword v136, v[46:47], off
	global_load_dword v137, v[46:47], off offset:256
	global_load_dwordx4 v[232:235], v[44:45], off offset:64
	s_addc_u32 s10, s10, 0
	s_cmp_ge_i32 s11, s1
	s_mov_b32 s20, s11
	s_waitcnt vmcnt(10)
	v_max_f32_e32 v39, v32, v32
	v_max_f32_e32 v55, v37, v39
	v_max_f32_e32 v37, v29, v29
	v_max_f32_e32 v39, v33, v33
	v_max_f32_e32 v57, v37, v39
	v_sub_f32_e32 v32, v32, v55
	v_sub_f32_e32 v33, v33, v57
	v_sub_f32_e32 v28, v28, v55
	v_mul_f32_e32 v32, 0x3e0293ee, v32
	v_sub_f32_e32 v29, v29, v57
	v_mul_f32_e32 v33, 0x3e0293ee, v33
	v_mul_f32_e32 v28, 0x3e0293ee, v28
	v_exp_f32_e32 v32, v32
	v_mul_f32_e32 v29, 0x3e0293ee, v29
	v_exp_f32_e32 v33, v33
	v_exp_f32_e32 v28, v28
	v_exp_f32_e32 v29, v29
	v_max_f32_e32 v37, v30, v30
	s_waitcnt vmcnt(6)
	v_pk_mul_f32 v[130:131], v[130:131], v[32:33]
	v_max_f32_e32 v39, v34, v34
	v_pk_fma_f32 v[0:1], v[0:1], v[28:29], v[130:131]
	s_waitcnt vmcnt(5)
	v_pk_mul_f32 v[130:131], v[126:127], v[32:33]
	s_waitcnt vmcnt(3)
	v_pk_mul_f32 v[126:127], v[134:135], v[32:33]
	global_load_dword v134, v180, s[6:7] offset:512
	global_load_dword v138, v[124:125], off offset:512
	global_load_dword v140, v[122:123], off offset:512
	global_load_dword v142, v[46:47], off offset:512
	global_load_dwordx4 v[148:151], v[44:45], off offset:32
	global_load_dword v135, v180, s[6:7] offset:768
	global_load_dword v139, v[124:125], off offset:768
	global_load_dword v141, v[122:123], off offset:768
	global_load_dword v143, v[46:47], off offset:768
	v_max_f32_e32 v186, v37, v39
	v_max_f32_e32 v37, v31, v31
	v_max_f32_e32 v39, v35, v35
	v_max_f32_e32 v188, v37, v39
	v_sub_f32_e32 v34, v34, v186
	v_sub_f32_e32 v35, v35, v188
	v_sub_f32_e32 v30, v30, v186
	v_mul_f32_e32 v34, 0x3e0293ee, v34
	v_sub_f32_e32 v31, v31, v188
	v_mul_f32_e32 v35, 0x3e0293ee, v35
	v_mul_f32_e32 v30, 0x3e0293ee, v30
	v_exp_f32_e32 v34, v34
	v_mul_f32_e32 v31, 0x3e0293ee, v31
	v_exp_f32_e32 v35, v35
	v_exp_f32_e32 v30, v30
	v_exp_f32_e32 v31, v31
	v_max_f32_e32 v37, v24, v24
	v_pk_mul_f32 v[132:133], v[132:133], v[34:35]
	v_pk_mul_f32 v[128:129], v[128:129], v[32:33]
	s_waitcnt vmcnt(9)
	v_pk_mul_f32 v[32:33], v[32:33], v[136:137]
	v_pk_fma_f32 v[2:3], v[2:3], v[30:31], v[132:133]
	v_pk_fma_f32 v[82:83], v[82:83], v[28:29], v[130:131]
	v_pk_fma_f32 v[76:77], v[76:77], v[28:29], v[128:129]
	v_pk_fma_f32 v[58:59], v[58:59], v[28:29], v[126:127]
	v_pk_fma_f32 v[66:67], v[66:67], v[28:29], v[32:33]
	v_mov_b32_e32 v28, v55
	v_mov_b32_e32 v29, v57
	s_waitcnt vmcnt(4)
	v_max_f32_e32 v39, v148, v148
	v_max_f32_e32 v189, v37, v39
	v_max_f32_e32 v37, v25, v25
	v_max_f32_e32 v39, v149, v149
	v_sub_f32_e32 v24, v24, v189
	v_max_f32_e32 v190, v37, v39
	v_mul_f32_e32 v24, 0x3e0293ee, v24
	v_sub_f32_e32 v25, v25, v190
	s_waitcnt vmcnt(3)
	v_pk_mul_f32 v[136:137], v[134:135], v[34:35]
	s_waitcnt vmcnt(2)
	v_pk_mul_f32 v[134:135], v[138:139], v[34:35]
	s_waitcnt vmcnt(1)
	v_pk_mul_f32 v[132:133], v[140:141], v[34:35]
	s_waitcnt vmcnt(0)
	v_pk_mul_f32 v[34:35], v[34:35], v[142:143]
	v_exp_f32_e32 v138, v24
	v_sub_f32_e32 v24, v148, v189
	global_load_dword v140, v180, s[6:7] offset:1024
	global_load_dword v142, v[124:125], off offset:1024
	global_load_dword v148, v[122:123], off offset:1024
	global_load_dword v156, v[46:47], off offset:1024
	v_mul_f32_e32 v25, 0x3e0293ee, v25
	global_load_dwordx4 v[152:155], v[44:45], off offset:1056
	v_exp_f32_e32 v139, v25
	v_sub_f32_e32 v25, v149, v190
	global_load_dword v141, v180, s[6:7] offset:1280
	global_load_dword v143, v[124:125], off offset:1280
	global_load_dword v149, v[122:123], off offset:1280
	global_load_dword v157, v[46:47], off offset:1280
	v_mul_f32_e32 v24, 0x3e0293ee, v24
	v_mul_f32_e32 v25, 0x3e0293ee, v25
	v_exp_f32_e32 v24, v24
	v_exp_f32_e32 v25, v25
	v_max_f32_e32 v37, v151, v151
	v_pk_fma_f32 v[84:85], v[84:85], v[30:31], v[136:137]
	v_pk_fma_f32 v[78:79], v[78:79], v[30:31], v[134:135]
	v_pk_fma_f32 v[60:61], v[60:61], v[30:31], v[132:133]
	v_pk_fma_f32 v[68:69], v[68:69], v[30:31], v[34:35]
	v_mov_b32_e32 v30, v186
	v_mov_b32_e32 v31, v188
	s_waitcnt vmcnt(4)
	v_pk_mul_f32 v[144:145], v[152:153], v[24:25]
	s_nop 0
	v_pk_fma_f32 v[4:5], v[4:5], v[138:139], v[144:145]
	s_waitcnt vmcnt(3)
	v_pk_mul_f32 v[146:147], v[140:141], v[24:25]
	s_waitcnt vmcnt(2)
	v_pk_mul_f32 v[144:145], v[142:143], v[24:25]
	s_waitcnt vmcnt(1)
	v_pk_mul_f32 v[142:143], v[148:149], v[24:25]
	s_waitcnt vmcnt(0)
; __device__ __forceinline__ int crow(int r, int hi) { return (r & 3) + 8 * (r >> 2) + 4 * hi; }
; __device__ __forceinline__ void merge_phase(char* lds, const Bases& bs, const float* nrm, const int tid, const int bid) {
;     ...
;         for (int sg = kf; sg <= kl; ++sg) {
;             const float* po = slot_po(bs, s0 + sg) + (size_t)wid * (QBLK * D) + (unsigned)lane;
;             const float* ml = bs.ML + (size_t)(s0 + sg) * 512 + wid * QBLK;
; #pragma unroll
;             for (int r = 0; r < 16; ++r) { const int row = crow(r, hi); const float ms = ml[row], ls = ml[256 + row];
;                 if (sg == kf) { mm[r] = ms; den[r] = ls;
; #pragma unroll
;                     for (int d0 = 0; d0 < 4; ++d0) o[d0][r] = po[(d0 * 16 + r) * 64]; }
;                 else { const float mn = fmaxf(mm[r], ms), ca = __builtin_amdgcn_exp2f((mm[r] - mn) * C2), cb = __builtin_amdgcn_exp2f((ms - mn) * C2);
;                     mm[r] = mn; den[r] = den[r] * ca + cb * ls;
; #pragma unroll
;                     for (int d0 = 0; d0 < 4; ++d0) o[d0][r] = o[d0][r] * ca + cb * po[(d0 * 16 + r) * 64]; } }
;         }
	v_pk_mul_f32 v[140:141], v[24:25], v[156:157]
	v_max_f32_e32 v24, v26, v26
	v_max_f32_e32 v25, v150, v150
	v_max_f32_e32 v191, v24, v25
	v_max_f32_e32 v25, v27, v27
	v_max_f32_e32 v192, v25, v37
	v_sub_f32_e32 v24, v26, v191
	v_sub_f32_e32 v25, v27, v192
	v_mul_f32_e32 v24, 0x3e0293ee, v24
	v_mul_f32_e32 v25, 0x3e0293ee, v25
	v_exp_f32_e32 v148, v24
	v_sub_f32_e32 v24, v150, v191
	global_load_dword v26, v180, s[6:7] offset:1536
	global_load_dword v150, v[124:125], off offset:1536
	global_load_dword v152, v[122:123], off offset:1536
	global_load_dword v158, v[46:47], off offset:1536
	v_exp_f32_e32 v149, v25
	v_sub_f32_e32 v25, v151, v192
	global_load_dword v27, v180, s[6:7] offset:1792
	global_load_dword v151, v[124:125], off offset:1792
	global_load_dword v153, v[122:123], off offset:1792
	global_load_dword v159, v[46:47], off offset:1792
	v_mul_f32_e32 v24, 0x3e0293ee, v24
	v_mul_f32_e32 v25, 0x3e0293ee, v25
	v_exp_f32_e32 v24, v24
	v_exp_f32_e32 v25, v25
	v_max_f32_e32 v37, v20, v20
	v_pk_fma_f32 v[88:89], v[88:89], v[138:139], v[146:147]
	v_pk_fma_f32 v[80:81], v[80:81], v[138:139], v[144:145]
	v_pk_mul_f32 v[154:155], v[154:155], v[24:25]
	v_pk_fma_f32 v[62:63], v[62:63], v[138:139], v[142:143]
	v_pk_fma_f32 v[6:7], v[6:7], v[148:149], v[154:155]
	v_pk_fma_f32 v[70:71], v[70:71], v[138:139], v[140:141]
	s_waitcnt vmcnt(3)
	v_pk_mul_f32 v[156:157], v[26:27], v[24:25]
	s_waitcnt vmcnt(2)
	v_pk_mul_f32 v[154:155], v[150:151], v[24:25]
	s_waitcnt vmcnt(1)
	v_pk_mul_f32 v[152:153], v[152:153], v[24:25]
	s_waitcnt vmcnt(0)
	v_pk_mul_f32 v[150:151], v[24:25], v[158:159]
	v_mov_b32_e32 v24, v232
	v_mov_b32_e32 v25, v233
	v_mov_b32_e32 v26, v234
	v_mov_b32_e32 v27, v235
	v_pk_fma_f32 v[92:93], v[92:93], v[148:149], v[156:157]
	v_pk_fma_f32 v[86:87], v[86:87], v[148:149], v[154:155]
	v_pk_fma_f32 v[64:65], v[64:65], v[148:149], v[152:153]
	v_pk_fma_f32 v[72:73], v[72:73], v[148:149], v[150:151]
	s_waitcnt vmcnt(0)
	v_max_f32_e32 v39, v24, v24
	v_max_f32_e32 v193, v37, v39
	v_max_f32_e32 v37, v21, v21
	v_max_f32_e32 v39, v25, v25
	v_sub_f32_e32 v20, v20, v193
	v_max_f32_e32 v206, v37, v39
	v_mul_f32_e32 v20, 0x3e0293ee, v20
	v_sub_f32_e32 v21, v21, v206
	v_exp_f32_e32 v158, v20
	v_sub_f32_e32 v20, v24, v193
	global_load_dword v24, v180, s[6:7] offset:2048
	global_load_dword v160, v[124:125], off offset:2048
	global_load_dword v170, v[122:123], off offset:2048
	global_load_dword v172, v[46:47], off offset:2048
	v_mul_f32_e32 v21, 0x3e0293ee, v21
	global_load_dwordx4 v[166:169], v[44:45], off offset:1088
	v_exp_f32_e32 v159, v21
	v_sub_f32_e32 v21, v25, v206
	global_load_dword v25, v180, s[6:7] offset:2304
	global_load_dword v161, v[124:125], off offset:2304
	global_load_dword v171, v[122:123], off offset:2304
	global_load_dword v173, v[46:47], off offset:2304
	v_mul_f32_e32 v20, 0x3e0293ee, v20
	v_mul_f32_e32 v21, 0x3e0293ee, v21
	v_exp_f32_e32 v20, v20
	v_exp_f32_e32 v21, v21
	v_max_f32_e32 v37, v27, v27
	s_waitcnt vmcnt(4)
	v_pk_mul_f32 v[162:163], v[166:167], v[20:21]
	s_nop 0
	v_pk_fma_f32 v[8:9], v[8:9], v[158:159], v[162:163]
	s_waitcnt vmcnt(3)
	v_pk_mul_f32 v[164:165], v[24:25], v[20:21]
	s_waitcnt vmcnt(2)
	v_pk_mul_f32 v[162:163], v[160:161], v[20:21]
	s_waitcnt vmcnt(1)
	v_pk_mul_f32 v[160:161], v[170:171], v[20:21]
	s_waitcnt vmcnt(0)
	v_pk_mul_f32 v[24:25], v[20:21], v[172:173]
	v_max_f32_e32 v20, v22, v22
	v_max_f32_e32 v21, v26, v26
	v_max_f32_e32 v207, v20, v21
	v_max_f32_e32 v21, v23, v23
	v_max_f32_e32 v208, v21, v37
	v_sub_f32_e32 v20, v22, v207
	v_sub_f32_e32 v21, v23, v208
	v_mul_f32_e32 v20, 0x3e0293ee, v20
	v_mul_f32_e32 v21, 0x3e0293ee, v21
	v_exp_f32_e32 v166, v20
	v_sub_f32_e32 v20, v26, v207
	global_load_dword v22, v180, s[6:7] offset:2560
	global_load_dword v26, v[124:125], off offset:2560
	global_load_dword v196, v[122:123], off offset:2560
	global_load_dword v198, v[46:47], off offset:2560
	v_exp_f32_e32 v167, v21
	v_sub_f32_e32 v21, v27, v208
	global_load_dword v23, v180, s[6:7] offset:2816
	global_load_dword v27, v[124:125], off offset:2816
	global_load_dword v197, v[122:123], off offset:2816
	global_load_dword v199, v[46:47], off offset:2816
	v_mul_f32_e32 v20, 0x3e0293ee, v20
	v_mul_f32_e32 v21, 0x3e0293ee, v21
	v_exp_f32_e32 v20, v20
	v_exp_f32_e32 v21, v21
	v_max_f32_e32 v37, v16, v16
	v_pk_fma_f32 v[94:95], v[94:95], v[158:159], v[164:165]
	v_pk_fma_f32 v[90:91], v[90:91], v[158:159], v[162:163]
	v_pk_mul_f32 v[168:169], v[168:169], v[20:21]
	v_pk_fma_f32 v[100:101], v[100:101], v[158:159], v[160:161]
	v_pk_fma_f32 v[10:11], v[10:11], v[166:167], v[168:169]
	v_pk_fma_f32 v[74:75], v[74:75], v[158:159], v[24:25]
	v_mov_b32_e32 v24, v189
	v_mov_b32_e32 v25, v190
	s_waitcnt vmcnt(3)
	v_pk_mul_f32 v[172:173], v[22:23], v[20:21]
	s_waitcnt vmcnt(2)
; __device__ __forceinline__ int crow(int r, int hi) { return (r & 3) + 8 * (r >> 2) + 4 * hi; }
; __device__ __forceinline__ void merge_phase(char* lds, const Bases& bs, const float* nrm, const int tid, const int bid) {
;     ...
;         for (int sg = kf; sg <= kl; ++sg) {
;             const float* po = slot_po(bs, s0 + sg) + (size_t)wid * (QBLK * D) + (unsigned)lane;
;             const float* ml = bs.ML + (size_t)(s0 + sg) * 512 + wid * QBLK;
; #pragma unroll
;             for (int r = 0; r < 16; ++r) { const int row = crow(r, hi); const float ms = ml[row], ls = ml[256 + row];
;                 if (sg == kf) { mm[r] = ms; den[r] = ls;
; #pragma unroll
;                     for (int d0 = 0; d0 < 4; ++d0) o[d0][r] = po[(d0 * 16 + r) * 64]; }
;                 else { const float mn = fmaxf(mm[r], ms), ca = __builtin_amdgcn_exp2f((mm[r] - mn) * C2), cb = __builtin_amdgcn_exp2f((ms - mn) * C2);
;                     mm[r] = mn; den[r] = den[r] * ca + cb * ls;
; #pragma unroll
;                     for (int d0 = 0; d0 < 4; ++d0) o[d0][r] = o[d0][r] * ca + cb * po[(d0 * 16 + r) * 64]; } }
;         }
	v_pk_mul_f32 v[170:171], v[26:27], v[20:21]
	s_waitcnt vmcnt(1)
	v_pk_mul_f32 v[168:169], v[196:197], v[20:21]
	s_waitcnt vmcnt(0)
	v_pk_mul_f32 v[26:27], v[20:21], v[198:199]
	global_load_dwordx4 v[20:23], v[44:45], off offset:96
	global_load_dword v212, v180, s[6:7] offset:3072
	global_load_dword v214, v[124:125], off offset:3072
	global_load_dword v216, v[122:123], off offset:3072
	global_load_dword v218, v[46:47], off offset:3072
	global_load_dwordx4 v[196:199], v[44:45], off offset:1120
	global_load_dword v213, v180, s[6:7] offset:3328
	global_load_dword v215, v[124:125], off offset:3328
	global_load_dword v217, v[122:123], off offset:3328
	global_load_dword v219, v[46:47], off offset:3328
	v_pk_fma_f32 v[106:107], v[106:107], v[166:167], v[172:173]
	v_pk_fma_f32 v[108:109], v[108:109], v[166:167], v[170:171]
	v_pk_fma_f32 v[102:103], v[102:103], v[166:167], v[168:169]
	v_pk_fma_f32 v[96:97], v[96:97], v[166:167], v[26:27]
	v_lshl_add_u64 v[44:45], v[44:45], 0, s[36:37]
	v_mov_b32_e32 v26, v191
	v_mov_b32_e32 v27, v192
	global_load_dword v41, v[122:123], off offset:3840
	s_waitcnt vmcnt(10)
	v_max_f32_e32 v39, v20, v20
	v_max_f32_e32 v209, v37, v39
	v_sub_f32_e32 v20, v20, v209
	v_mul_f32_e32 v20, 0x3e0293ee, v20
	v_exp_f32_e32 v210, v20
	v_max_f32_e32 v20, v17, v17
	v_max_f32_e32 v37, v21, v21
	v_max_f32_e32 v20, v20, v37
	v_sub_f32_e32 v21, v21, v20
	v_sub_f32_e32 v16, v16, v209
	v_sub_f32_e32 v17, v17, v20
	v_mul_f32_e32 v21, 0x3e0293ee, v21
	v_mul_f32_e32 v16, 0x3e0293ee, v16
	v_mul_f32_e32 v17, 0x3e0293ee, v17
	v_exp_f32_e32 v211, v21
	v_exp_f32_e32 v16, v16
	v_exp_f32_e32 v17, v17
	v_max_f32_e32 v21, v18, v18
	v_max_f32_e32 v37, v22, v22
	v_max_f32_e32 v21, v21, v37
	v_sub_f32_e32 v22, v22, v21
	s_waitcnt vmcnt(5)
	v_pk_mul_f32 v[196:197], v[196:197], v[210:211]
	v_mul_f32_e32 v22, 0x3e0293ee, v22
	v_pk_fma_f32 v[12:13], v[12:13], v[16:17], v[196:197]
	s_waitcnt vmcnt(4)
	v_pk_mul_f32 v[196:197], v[212:213], v[210:211]
	s_waitcnt vmcnt(3)
	v_pk_mul_f32 v[212:213], v[214:215], v[210:211]
	s_waitcnt vmcnt(2)
	v_pk_mul_f32 v[214:215], v[216:217], v[210:211]
	v_exp_f32_e32 v216, v22
	global_load_dword v22, v180, s[6:7] offset:3584
	global_load_dword v226, v[124:125], off offset:3584
	global_load_dword v227, v[122:123], off offset:3584
	global_load_dword v228, v[46:47], off offset:3584
	global_load_dword v229, v180, s[6:7] offset:3840
	global_load_dword v230, v[46:47], off offset:3840
	s_waitcnt vmcnt(7)
	v_pk_mul_f32 v[210:211], v[210:211], v[218:219]
	v_max_f32_e32 v37, v23, v23
	global_load_dword v39, v[124:125], off offset:3840
	v_sub_f32_e32 v18, v18, v21
	v_mul_f32_e32 v18, 0x3e0293ee, v18
	v_exp_f32_e32 v18, v18
	v_pk_fma_f32 v[110:111], v[110:111], v[16:17], v[196:197]
	v_pk_fma_f32 v[112:113], v[112:113], v[16:17], v[212:213]
	v_pk_fma_f32 v[104:105], v[104:105], v[16:17], v[214:215]
	v_mul_f32_e32 v114, v114, v18
	v_mul_f32_e32 v116, v116, v18
	v_mul_f32_e32 v118, v118, v18
	v_mul_f32_e32 v120, v120, v18
	v_pk_fma_f32 v[98:99], v[98:99], v[16:17], v[210:211]
	v_mov_b32_e32 v16, v209
	v_mov_b32_e32 v17, v20
	v_mov_b32_e32 v20, v193
	s_waitcnt vmcnt(6)
	v_mul_f32_e32 v218, v22, v216
	s_waitcnt vmcnt(5)
	v_mul_f32_e32 v220, v226, v216
	s_waitcnt vmcnt(4)
	v_mul_f32_e32 v222, v227, v216
	s_waitcnt vmcnt(3)
	v_mul_f32_e32 v224, v216, v228
	v_max_f32_e32 v22, v19, v19
	v_max_f32_e32 v22, v22, v37
	v_sub_f32_e32 v19, v19, v22
	v_sub_f32_e32 v23, v23, v22
	v_mul_f32_e32 v19, 0x3e0293ee, v19
	v_mul_f32_e32 v23, 0x3e0293ee, v23
	v_exp_f32_e32 v19, v19
	v_exp_f32_e32 v217, v23
	v_mov_b32_e32 v23, v208
	v_pk_mul_f32 v[198:199], v[198:199], v[216:217]
	v_mov_b32_e32 v216, v19
	v_mov_b32_e32 v43, v217
	v_pk_fma_f32 v[14:15], v[14:15], v[18:19], v[198:199]
	s_waitcnt vmcnt(0)
	v_mov_b32_e32 v37, v229
	v_pk_mul_f32 v[36:37], v[36:37], v[216:217]
	s_nop 0
	v_mov_b32_e32 v115, v36
	v_mov_b32_e32 v219, v37
	v_pk_mul_f32 v[36:37], v[38:39], v[216:217]
	v_pk_add_f32 v[114:115], v[114:115], v[218:219]
	v_mov_b32_e32 v117, v36
	v_mov_b32_e32 v221, v37
	v_pk_mul_f32 v[36:37], v[40:41], v[216:217]
	v_pk_add_f32 v[116:117], v[116:117], v[220:221]
	v_mov_b32_e32 v223, v37
	v_mov_b32_e32 v37, v230
	v_mov_b32_e32 v119, v36
	v_mov_b32_e32 v36, v19
	v_pk_add_f32 v[118:119], v[118:119], v[222:223]
	v_mov_b32_e32 v38, v117
	v_mov_b32_e32 v40, v119
	s_waitcnt vmcnt(0)
	v_pk_mul_f32 v[18:19], v[42:43], v[36:37]
	s_nop 0
	v_mov_b32_e32 v121, v18
	v_mov_b32_e32 v225, v19
	v_pk_add_f32 v[120:121], v[120:121], v[224:225]
	v_mov_b32_e32 v36, v115
	v_mov_b32_e32 v42, v121
	v_mov_b32_e32 v18, v21
	v_mov_b32_e32 v19, v22
	v_mov_b32_e32 v22, v207
	v_mov_b32_e32 v21, v206
	s_cbranch_scc0 .LBB0_113
	s_movk_i32 s97, 0x3000
	s_movk_i32 s95, 0x2000
	s_branch .LBB0_88
